# speedup vs baseline: 1.0070x; 1.0070x over previous
; __device__ __forceinline__ void partialSM(f32x16& p0, f32x16& p1, float& m_reg, float& mn, float& alpha) {
;     float pmax = p0[0];
; #pragma unroll
;     for (int r = 1; r < 16; ++r) pmax = fmaxf(pmax, p0[r]);
; #pragma unroll
;     for (int r = 0; r < 16; ++r) pmax = fmaxf(pmax, p1[r]);
;     { auto rr = __builtin_amdgcn_permlane32_swap(__float_as_uint(pmax), __float_as_uint(pmax), false, false);
;       pmax = fmaxf(__uint_as_float(rr[0]), __uint_as_float(rr[1])); }
;     constexpr float C2 = 1.4426950408889634f * ASCALE;
;     if (__builtin_expect(__all((pmax - m_reg) * ASCALE <= ATHR), 1)) { mn = m_reg; alpha = 1.f; }
;     else { mn = fmaxf(m_reg, pmax); alpha = __builtin_amdgcn_exp2f((m_reg - mn) * C2); m_reg = mn; }
.LBB0_410:
	s_nop 0
	s_waitcnt lgkmcnt(4)
	v_mfma_f32_32x32x16_bf16 v[50:65], v[166:169], v[214:217], v[50:65]
	ds_read_b64_tr_b16 v[214:215], v194 offset:0x200
	ds_read_b64_tr_b16 v[216:217], v194 offset:0xa00
	v_max_f32_e32 v0, v82, v83
	v_mfma_f32_32x32x16_bf16 v[50:65], v[170:173], v[218:221], v[50:65]
	ds_read_b64_tr_b16 v[218:219], v194 offset:0x1200
	ds_read_b64_tr_b16 v[220:221], v194 offset:0x1a00
	v_max3_f32 v0, v0, v84, v85
	v_max3_f32 v0, v0, v86, v87
	s_waitcnt lgkmcnt(4)
	v_mfma_f32_32x32x16_bf16 v[50:65], v[174:177], v[222:225], v[50:65]
	ds_read_b64_tr_b16 v[222:223], v194 offset:0x2200
	ds_read_b64_tr_b16 v[224:225], v194 offset:0x2a00
	v_max3_f32 v0, v0, v88, v89
	v_max3_f32 v0, v0, v90, v91
	v_mfma_f32_32x32x16_bf16 v[50:65], v[178:181], v[226:229], v[50:65]
	ds_read_b64_tr_b16 v[226:227], v194 offset:0x3200
	ds_read_b64_tr_b16 v[228:229], v194 offset:0x3a00
	v_max3_f32 v0, v0, v92, v93
	v_max3_f32 v0, v0, v94, v95
	v_max3_f32 v0, v0, v96, v97
	s_waitcnt lgkmcnt(4)
	v_mfma_f32_32x32x16_bf16 v[34:49], v[166:169], v[214:217], v[34:49]
	ds_read_b64_tr_b16 v[214:215], v194 offset:0x400
	ds_read_b64_tr_b16 v[216:217], v194 offset:0xc00
	v_max3_f32 v0, v0, v66, v67
	v_max3_f32 v0, v0, v68, v69
	v_mfma_f32_32x32x16_bf16 v[34:49], v[170:173], v[218:221], v[34:49]
	ds_read_b64_tr_b16 v[218:219], v194 offset:0x1400
	ds_read_b64_tr_b16 v[220:221], v194 offset:0x1c00
	v_max3_f32 v0, v0, v70, v71
	v_max3_f32 v0, v0, v72, v73
	s_waitcnt lgkmcnt(4)
	v_mfma_f32_32x32x16_bf16 v[34:49], v[174:177], v[222:225], v[34:49]
	ds_read_b64_tr_b16 v[222:223], v194 offset:0x2400
	ds_read_b64_tr_b16 v[224:225], v194 offset:0x2c00
	v_max3_f32 v0, v0, v74, v75
	v_max3_f32 v0, v0, v76, v77
	v_max3_f32 v0, v0, v78, v79
	v_mfma_f32_32x32x16_bf16 v[34:49], v[178:181], v[226:229], v[34:49]
	ds_read_b64_tr_b16 v[226:227], v194 offset:0x3400
	ds_read_b64_tr_b16 v[228:229], v194 offset:0x3c00
	v_max3_f32 v0, v0, v80, v81
	v_mov_b32_e32 v190, v0
	s_waitcnt lgkmcnt(4)
	v_mfma_f32_32x32x16_bf16 v[18:33], v[166:169], v[214:217], v[18:33]
	ds_read_b64_tr_b16 v[214:215], v194 offset:0x600
	ds_read_b64_tr_b16 v[216:217], v194 offset:0xe00
	v_permlane32_swap_b32_e32 v0, v190
	v_mfma_f32_32x32x16_bf16 v[18:33], v[170:173], v[218:221], v[18:33]
	ds_read_b64_tr_b16 v[218:219], v194 offset:0x1600
	ds_read_b64_tr_b16 v[220:221], v194 offset:0x1e00
	v_max_f32_e32 v0, v0, v190
	s_waitcnt lgkmcnt(4)
	v_mfma_f32_32x32x16_bf16 v[18:33], v[174:177], v[222:225], v[18:33]
	ds_read_b64_tr_b16 v[222:223], v194 offset:0x2600
	ds_read_b64_tr_b16 v[224:225], v194 offset:0x2e00
	v_sub_f32_e32 v190, v0, v210
	v_mfma_f32_32x32x16_bf16 v[18:33], v[178:181], v[226:229], v[18:33]
	ds_read_b64_tr_b16 v[226:227], v194 offset:0x3600
	ds_read_b64_tr_b16 v[228:229], v194 offset:0x3e00
	s_waitcnt lgkmcnt(4)
	v_mfma_f32_32x32x16_bf16 v[2:17], v[166:169], v[214:217], v[2:17]
	s_waitcnt vmcnt(2)
	v_add_u32_e32 v192, 0x10800, v206
	ds_write_b128 v207, v[154:157] offset:32768
	ds_write_b128 v207, v[158:161] offset:41472
	ds_write_b128 v192, v[162:165]
	v_mul_f32_e32 v190, 0x3d93cd3a, v190
	v_mfma_f32_32x32x16_bf16 v[2:17], v[170:173], v[218:221], v[2:17]
	v_cmp_ge_f32_e32 vcc, 0x41000000, v190
	s_waitcnt lgkmcnt(3)
	v_mfma_f32_32x32x16_bf16 v[2:17], v[174:177], v[222:225], v[2:17]
	s_cmp_eq_u64 vcc, exec
	s_cselect_b64 s[6:7], -1, 0
	v_mfma_f32_32x32x16_bf16 v[2:17], v[178:181], v[226:229], v[2:17]
	s_barrier
	s_waitcnt vmcnt(0)
	ds_write_b128 v202, v[146:149]
	ds_write_b128 v203, v[150:153]
	s_and_b64 vcc, exec, s[6:7]
	s_cbranch_vccnz .Lfast1
	v_max_f32_e32 v0, v210, v0
	v_sub_f32_e32 v191, v210, v0
	v_mul_f32_e32 v191, 0x3dd53b94, v191
	v_exp_f32_e32 v213, v191
	v_mov_b32_e32 v210, v0
	v_cmp_gt_f32_e32 vcc, 1.0, v213
	s_cbranch_vccz .LBB0_414
	s_and_saveexec_b64 s[8:9], s[4:5]
	ds_write_b32 v195, v213 offset:128
	s_or_b64 exec, exec, s[8:9]
	s_waitcnt lgkmcnt(0)
	ds_read_b128 v[166:169], v198 offset:224
	ds_read_b128 v[170:173], v198 offset:192
	ds_read_b128 v[174:177], v198 offset:160
	ds_read_b128 v[178:181], v198 offset:128
	s_waitcnt lgkmcnt(3)
	v_pk_mul_f32 v[64:65], v[64:65], v[168:169]
	s_waitcnt lgkmcnt(2)
	v_pk_mul_f32 v[60:61], v[60:61], v[172:173]
	s_waitcnt lgkmcnt(1)
	v_pk_mul_f32 v[56:57], v[56:57], v[176:177]
	s_waitcnt lgkmcnt(0)
	v_pk_mul_f32 v[52:53], v[52:53], v[180:181]
	v_pk_mul_f32 v[62:63], v[62:63], v[166:167]
	v_pk_mul_f32 v[58:59], v[58:59], v[170:171]
	v_pk_mul_f32 v[54:55], v[54:55], v[174:175]
	v_pk_mul_f32 v[50:51], v[50:51], v[178:179]
	v_pk_mul_f32 v[48:49], v[48:49], v[168:169]
	v_pk_mul_f32 v[44:45], v[44:45], v[172:173]
	v_pk_mul_f32 v[40:41], v[40:41], v[176:177]
	v_pk_mul_f32 v[36:37], v[36:37], v[180:181]
	v_pk_mul_f32 v[46:47], v[46:47], v[166:167]
	v_pk_mul_f32 v[42:43], v[42:43], v[170:171]
	v_pk_mul_f32 v[38:39], v[38:39], v[174:175]
	v_pk_mul_f32 v[34:35], v[34:35], v[178:179]
	v_pk_mul_f32 v[32:33], v[32:33], v[168:169]
	v_pk_mul_f32 v[28:29], v[28:29], v[172:173]
	v_pk_mul_f32 v[24:25], v[24:25], v[176:177]
	v_pk_mul_f32 v[20:21], v[20:21], v[180:181]
	v_pk_mul_f32 v[30:31], v[30:31], v[166:167]
	v_pk_mul_f32 v[26:27], v[26:27], v[170:171]
	v_pk_mul_f32 v[22:23], v[22:23], v[174:175]
	v_pk_mul_f32 v[18:19], v[18:19], v[178:179]
	v_pk_mul_f32 v[16:17], v[16:17], v[168:169]
	v_pk_mul_f32 v[12:13], v[12:13], v[172:173]
	v_pk_mul_f32 v[8:9], v[8:9], v[176:177]
	v_pk_mul_f32 v[4:5], v[4:5], v[180:181]
	v_pk_mul_f32 v[14:15], v[14:15], v[166:167]
	v_pk_mul_f32 v[10:11], v[10:11], v[170:171]
	v_pk_mul_f32 v[6:7], v[6:7], v[174:175]
	v_pk_mul_f32 v[2:3], v[2:3], v[178:179]
	s_branch .LBB0_414

; __device__ __forceinline__ void partialSM(f32x16& p0, f32x16& p1, float& m_reg, float& mn, float& alpha) {
;     ...
;     const float mnL = -mn * C2;
; #pragma unroll
;     for (int r = 0; r < 16; ++r) p0[r] = fmaf(p0[r], C2, mnL);
; #pragma unroll
;     for (int r = 0; r < 16; ++r) p1[r] = fmaf(p1[r], C2, mnL);
; __device__ __forceinline__ void attn_block(const ABlk& cur, char* lds, ASeam& Sm, const int tid, const int wv) {
;     ...
;     for (int t = 1; t + 1 < NT; t += 2) {
;         HALF_STEP(pB0, pB1, mnB, alB, pA0, pA1, alA, t, 1, 0, 0);
;         HALF_STEP(pA0, pA1, mnA, alA, pB0, pB1, alB, t + 1, 0, 1, 1);
.LBB0_424:
	s_waitcnt vmcnt(0)
	v_mul_f32_e32 v148, 0xbdd53b94, v210
	s_addk_i32 s70, 0x80
	v_fmamk_f32 v166, v82, 0x3dd53b94, v148
	v_fmamk_f32 v175, v83, 0x3dd53b94, v148
	v_fmamk_f32 v167, v84, 0x3dd53b94, v148
	v_fmamk_f32 v176, v85, 0x3dd53b94, v148
	v_fmamk_f32 v168, v86, 0x3dd53b94, v148
	v_fmamk_f32 v177, v87, 0x3dd53b94, v148
	v_fmamk_f32 v169, v88, 0x3dd53b94, v148
	v_fmamk_f32 v174, v89, 0x3dd53b94, v148
	v_fmamk_f32 v165, v90, 0x3dd53b94, v148
	v_fmamk_f32 v170, v91, 0x3dd53b94, v148
	v_fmamk_f32 v171, v92, 0x3dd53b94, v148
	v_fmamk_f32 v172, v93, 0x3dd53b94, v148
	v_fmamk_f32 v162, v94, 0x3dd53b94, v148
	v_fmamk_f32 v164, v95, 0x3dd53b94, v148
	v_fmamk_f32 v163, v96, 0x3dd53b94, v148
	v_fmamk_f32 v173, v97, 0x3dd53b94, v148
	s_add_u32 s76, s76, 0x8000
	s_addc_u32 s77, s77, 0
	v_pk_fma_f32 v[160:161], v[66:67], s[84:85], v[148:149] op_sel_hi:[1,0,0]
	v_add_f32_e32 v66, v211, v212
	s_add_u32 s88, s88, 0x4000
	v_fmac_f32_e32 v66, v208, v196
	v_add_f32_e32 v196, v215, v216
	s_addc_u32 s89, s89, 0
	s_add_i32 s82, s82, 2
	v_pk_fma_f32 v[158:159], v[68:69], s[84:85], v[148:149] op_sel_hi:[1,0,0]
	v_pk_fma_f32 v[154:155], v[70:71], s[84:85], v[148:149] op_sel_hi:[1,0,0]
	v_pk_fma_f32 v[150:151], v[72:73], s[84:85], v[148:149] op_sel_hi:[1,0,0]
	v_pk_fma_f32 v[146:147], v[74:75], s[84:85], v[148:149] op_sel_hi:[1,0,0]
	v_pk_fma_f32 v[156:157], v[76:77], s[84:85], v[148:149] op_sel_hi:[1,0,0]
	v_pk_fma_f32 v[152:153], v[78:79], s[84:85], v[148:149] op_sel_hi:[1,0,0]
	v_pk_fma_f32 v[148:149], v[80:81], s[84:85], v[148:149] op_sel_hi:[1,0,0]
	v_fmac_f32_e32 v196, v66, v213
	s_cmp_ge_u32 s82, s83
	v_add_u32_e32 v209, 0xffffff80, v209
	v_mov_b32_e32 v208, v0
	s_waitcnt lgkmcnt(0)
	s_cbranch_scc1 .Lexit_bar
	s_branch .Lhead_bar
